# lever 7 instruction selection: glapre gate loop rewritten on v_pk_fma_f32/v_pk_mul_f32 over token pairs (pair-interleaved lrs layout in LDS, log-sigmoid of previous pair interleaved), replaces the sca
# speedup vs baseline: 1.0016x; 1.0016x over previous
.LBB0_609:
	s_lshl_b32 s0, s36, 3
	s_and_b32 s38, s0, 0xffffffc0
	s_and_saveexec_b64 s[62:63], s[2:3]
	s_cbranch_execz .LBB0_611
	s_ashr_i32 s39, s38, 31
	s_lshl_b64 s[64:65], s[38:39], 6
	v_lshl_add_u64 v[18:19], v[52:53], 0, s[64:65]
	global_load_dwordx4 v[18:21], v[18:19], off
	s_waitcnt vmcnt(0)
	v_and_b32_e32 v22, 48, v72
	v_lshlrev_b32_e32 v22, 1, v22
	v_and_b32_e32 v23, 64, v72
	v_lshrrev_b32_e32 v23, 4, v23
	v_or_b32_e32 v22, v22, v23
	v_and_b32_e32 v23, 0xffffff80, v72
	v_or_b32_e32 v22, v22, v23
	ds_write_b32 v22, v18
	ds_write_b32 v22, v19 offset:8
	ds_write_b32 v22, v20 offset:16
	ds_write_b32 v22, v21 offset:24
.LBB0_611:
	s_or_b64 exec, exec, s[62:63]
	s_lshl_b32 s0, s36, 8
	s_and_b32 s0, s0, 0x700
	s_lshl_b32 s0, s0, 1
	s_add_u32 s62, s56, s0
	s_addc_u32 s63, s57, 0
	v_mov_b32_e32 v69, v1
	v_lshl_add_u64 v[42:43], s[62:63], 0, v[68:69]
	v_add_u32_e32 v0, s38, v73
	v_mad_i64_i32 v[18:19], s[64:65], v0, s80, v[42:43]
	v_add_co_u32_e32 v22, vcc, s81, v18
	v_add_u32_e32 v0, s38, v74
	s_nop 0
	v_addc_co_u32_e32 v23, vcc, 0, v19, vcc
	v_mad_i64_i32 v[26:27], s[64:65], v0, s80, v[42:43]
	v_add_co_u32_e32 v30, vcc, s81, v26
	v_add_u32_e32 v0, s38, v75
	s_nop 0
	v_addc_co_u32_e32 v31, vcc, 0, v27, vcc
	v_mad_i64_i32 v[34:35], s[64:65], v0, s80, v[42:43]
	v_add_co_u32_e32 v38, vcc, s81, v34
	v_add_u32_e32 v0, s38, v76
	s_nop 0
	v_addc_co_u32_e32 v39, vcc, 0, v35, vcc
	v_mad_i64_i32 v[42:43], s[64:65], v0, s80, v[42:43]
	v_add_co_u32_e32 v46, vcc, s81, v42
	global_load_dwordx4 v[18:21], v[18:19], off
	s_nop 0
	global_load_dwordx4 v[22:25], v[22:23], off
	v_addc_co_u32_e32 v47, vcc, 0, v43, vcc
	global_load_dwordx4 v[26:29], v[26:27], off
	s_nop 0
	global_load_dwordx4 v[30:33], v[30:31], off
	s_nop 0
	global_load_dwordx4 v[34:37], v[34:35], off
	s_nop 0
	global_load_dwordx4 v[38:41], v[38:39], off
	s_nop 0
	global_load_dwordx4 v[42:45], v[42:43], off
	s_nop 0
	global_load_dwordx4 v[46:49], v[46:47], off
	s_waitcnt lgkmcnt(0)
	s_barrier
	ds_read_b128 v[120:123], v77
	ds_read_b128 v[124:127], v77 offset:16
	ds_read_b128 v[128:131], v77 offset:32
	ds_read_b128 v[132:135], v77 offset:48
	ds_read_b128 v[136:139], v77 offset:64
	ds_read_b128 v[140:143], v77 offset:80
	ds_read_b128 v[144:147], v77 offset:96
	ds_read_b128 v[148:151], v77 offset:112
	s_waitcnt vmcnt(8)
	s_waitcnt lgkmcnt(0)
	ds_read_b128 v[152:155], v77 offset:128
	ds_read_b128 v[156:159], v77 offset:144
	ds_read_b128 v[160:163], v77 offset:160
	ds_read_b128 v[164:167], v77 offset:176
	ds_read_b128 v[168:171], v77 offset:192
	ds_read_b128 v[172:175], v77 offset:208
	ds_read_b128 v[176:179], v77 offset:224
	ds_read_b128 v[180:183], v77 offset:240
	v_pk_fma_f32 v[110:111], v[120:121], v[2:3], v[78:79] op_sel:[0,0,1] op_sel_hi:[1,0,1]
	v_pk_mul_f32 v[112:113], v[128:129], v[6:7] op_sel:[0,0] op_sel_hi:[1,0]
	v_pk_mul_f32 v[114:115], v[136:137], v[10:11] op_sel:[0,0] op_sel_hi:[1,0]
	v_pk_mul_f32 v[116:117], v[144:145], v[14:15] op_sel:[0,0] op_sel_hi:[1,0]
	v_pk_fma_f32 v[110:111], v[122:123], v[2:3], v[110:111] op_sel:[0,1,0] op_sel_hi:[1,1,1]
	v_pk_fma_f32 v[112:113], v[130:131], v[6:7], v[112:113] op_sel:[0,1,0] op_sel_hi:[1,1,1]
	v_pk_fma_f32 v[114:115], v[138:139], v[10:11], v[114:115] op_sel:[0,1,0] op_sel_hi:[1,1,1]
	v_pk_fma_f32 v[116:117], v[146:147], v[14:15], v[116:117] op_sel:[0,1,0] op_sel_hi:[1,1,1]
	v_pk_fma_f32 v[110:111], v[124:125], v[4:5], v[110:111] op_sel:[0,0,0] op_sel_hi:[1,0,1]
	v_pk_fma_f32 v[112:113], v[132:133], v[8:9], v[112:113] op_sel:[0,0,0] op_sel_hi:[1,0,1]
	v_pk_fma_f32 v[114:115], v[140:141], v[12:13], v[114:115] op_sel:[0,0,0] op_sel_hi:[1,0,1]
	v_pk_fma_f32 v[116:117], v[148:149], v[16:17], v[116:117] op_sel:[0,0,0] op_sel_hi:[1,0,1]
	v_pk_fma_f32 v[110:111], v[126:127], v[4:5], v[110:111] op_sel:[0,1,0] op_sel_hi:[1,1,1]
	v_pk_fma_f32 v[112:113], v[134:135], v[8:9], v[112:113] op_sel:[0,1,0] op_sel_hi:[1,1,1]
	v_pk_fma_f32 v[114:115], v[142:143], v[12:13], v[114:115] op_sel:[0,1,0] op_sel_hi:[1,1,1]
	v_pk_fma_f32 v[116:117], v[150:151], v[16:17], v[116:117] op_sel:[0,1,0] op_sel_hi:[1,1,1]
	v_pk_add_f32 v[110:111], v[110:111], v[112:113]
	v_pk_add_f32 v[114:115], v[114:115], v[116:117]
	s_nop 0
	v_pk_add_f32 v[190:191], v[110:111], v[114:115]
	s_waitcnt lgkmcnt(0)
	ds_read_b128 v[120:123], v77 offset:256
	ds_read_b128 v[124:127], v77 offset:272
	ds_read_b128 v[128:131], v77 offset:288
	ds_read_b128 v[132:135], v77 offset:304
	ds_read_b128 v[136:139], v77 offset:320
	ds_read_b128 v[140:143], v77 offset:336
	ds_read_b128 v[144:147], v77 offset:352
	ds_read_b128 v[148:151], v77 offset:368
	v_pk_fma_f32 v[110:111], v[152:153], v[2:3], v[78:79] op_sel:[0,0,1] op_sel_hi:[1,0,1]
	v_mul_f32_e64 v192, |v190|, s82
	v_pk_mul_f32 v[112:113], v[160:161], v[6:7] op_sel:[0,0] op_sel_hi:[1,0]
	v_mul_f32_e64 v193, |v191|, s82
	v_pk_mul_f32 v[114:115], v[168:169], v[10:11] op_sel:[0,0] op_sel_hi:[1,0]
	v_exp_f32_e32 v192, v192
	v_pk_mul_f32 v[116:117], v[176:177], v[14:15] op_sel:[0,0] op_sel_hi:[1,0]
	v_exp_f32_e32 v193, v193
	v_pk_fma_f32 v[110:111], v[154:155], v[2:3], v[110:111] op_sel:[0,1,0] op_sel_hi:[1,1,1]
	v_max_f32_e64 v194, -v190, 0
	v_pk_fma_f32 v[112:113], v[162:163], v[6:7], v[112:113] op_sel:[0,1,0] op_sel_hi:[1,1,1]
	v_max_f32_e64 v195, -v191, 0
	v_pk_fma_f32 v[114:115], v[170:171], v[10:11], v[114:115] op_sel:[0,1,0] op_sel_hi:[1,1,1]
	v_add_f32_e32 v192, 1.0, v192
	v_pk_fma_f32 v[116:117], v[178:179], v[14:15], v[116:117] op_sel:[0,1,0] op_sel_hi:[1,1,1]
	v_add_f32_e32 v193, 1.0, v193
	v_pk_fma_f32 v[110:111], v[156:157], v[4:5], v[110:111] op_sel:[0,0,0] op_sel_hi:[1,0,1]
	v_log_f32_e32 v192, v192
	v_pk_fma_f32 v[112:113], v[164:165], v[8:9], v[112:113] op_sel:[0,0,0] op_sel_hi:[1,0,1]
	v_log_f32_e32 v193, v193
	v_pk_fma_f32 v[114:115], v[172:173], v[12:13], v[114:115] op_sel:[0,0,0] op_sel_hi:[1,0,1]
	s_nop 0
	v_pk_fma_f32 v[116:117], v[180:181], v[16:17], v[116:117] op_sel:[0,0,0] op_sel_hi:[1,0,1]
	v_fmac_f32_e32 v194, 0x3f317218, v192
	v_pk_fma_f32 v[110:111], v[158:159], v[4:5], v[110:111] op_sel:[0,1,0] op_sel_hi:[1,1,1]
	v_fmac_f32_e32 v195, 0x3f317218, v193
	v_pk_fma_f32 v[112:113], v[166:167], v[8:9], v[112:113] op_sel:[0,1,0] op_sel_hi:[1,1,1]
	v_fma_f32 v86, v194, s83, 0
	v_pk_fma_f32 v[114:115], v[174:175], v[12:13], v[114:115] op_sel:[0,1,0] op_sel_hi:[1,1,1]
	v_fmamk_f32 v0, v195, 0xbd800000, v86
	v_pk_fma_f32 v[116:117], v[182:183], v[16:17], v[116:117] op_sel:[0,1,0] op_sel_hi:[1,1,1]
	v_pk_add_f32 v[110:111], v[110:111], v[112:113]
	v_pk_add_f32 v[114:115], v[114:115], v[116:117]
	s_nop 0
	v_pk_add_f32 v[198:199], v[110:111], v[114:115]
	s_waitcnt lgkmcnt(0)
	ds_read_b128 v[152:155], v77 offset:384
	ds_read_b128 v[156:159], v77 offset:400
	ds_read_b128 v[160:163], v77 offset:416
	ds_read_b128 v[164:167], v77 offset:432
	ds_read_b128 v[168:171], v77 offset:448
	ds_read_b128 v[172:175], v77 offset:464
	ds_read_b128 v[176:179], v77 offset:480
	ds_read_b128 v[180:183], v77 offset:496
	v_pk_fma_f32 v[110:111], v[120:121], v[2:3], v[78:79] op_sel:[0,0,1] op_sel_hi:[1,0,1]
	v_mul_f32_e64 v200, |v198|, s82
	v_pk_mul_f32 v[112:113], v[128:129], v[6:7] op_sel:[0,0] op_sel_hi:[1,0]
	v_mul_f32_e64 v201, |v199|, s82
	v_pk_mul_f32 v[114:115], v[136:137], v[10:11] op_sel:[0,0] op_sel_hi:[1,0]
	v_exp_f32_e32 v200, v200
	v_pk_mul_f32 v[116:117], v[144:145], v[14:15] op_sel:[0,0] op_sel_hi:[1,0]
	v_exp_f32_e32 v201, v201
	v_pk_fma_f32 v[110:111], v[122:123], v[2:3], v[110:111] op_sel:[0,1,0] op_sel_hi:[1,1,1]
	v_max_f32_e64 v202, -v198, 0
	v_pk_fma_f32 v[112:113], v[130:131], v[6:7], v[112:113] op_sel:[0,1,0] op_sel_hi:[1,1,1]
	v_max_f32_e64 v203, -v199, 0
	v_pk_fma_f32 v[114:115], v[138:139], v[10:11], v[114:115] op_sel:[0,1,0] op_sel_hi:[1,1,1]
	v_add_f32_e32 v200, 1.0, v200
	v_pk_fma_f32 v[116:117], v[146:147], v[14:15], v[116:117] op_sel:[0,1,0] op_sel_hi:[1,1,1]
	v_add_f32_e32 v201, 1.0, v201
	v_pk_fma_f32 v[110:111], v[124:125], v[4:5], v[110:111] op_sel:[0,0,0] op_sel_hi:[1,0,1]
	v_log_f32_e32 v200, v200
	v_pk_fma_f32 v[112:113], v[132:133], v[8:9], v[112:113] op_sel:[0,0,0] op_sel_hi:[1,0,1]
	v_log_f32_e32 v201, v201
	v_pk_fma_f32 v[114:115], v[140:141], v[12:13], v[114:115] op_sel:[0,0,0] op_sel_hi:[1,0,1]
	s_nop 0
	v_pk_fma_f32 v[116:117], v[148:149], v[16:17], v[116:117] op_sel:[0,0,0] op_sel_hi:[1,0,1]
	v_fmac_f32_e32 v202, 0x3f317218, v200
	v_pk_fma_f32 v[110:111], v[126:127], v[4:5], v[110:111] op_sel:[0,1,0] op_sel_hi:[1,1,1]
	v_fmac_f32_e32 v203, 0x3f317218, v201
	v_pk_fma_f32 v[112:113], v[134:135], v[8:9], v[112:113] op_sel:[0,1,0] op_sel_hi:[1,1,1]
	v_fmamk_f32 v69, v202, 0xbd800000, v0
	v_pk_fma_f32 v[114:115], v[142:143], v[12:13], v[114:115] op_sel:[0,1,0] op_sel_hi:[1,1,1]
	v_fmamk_f32 v81, v203, 0xbd800000, v69
	v_pk_fma_f32 v[116:117], v[150:151], v[16:17], v[116:117] op_sel:[0,1,0] op_sel_hi:[1,1,1]
	v_pk_add_f32 v[110:111], v[110:111], v[112:113]
	v_pk_add_f32 v[114:115], v[114:115], v[116:117]
	s_nop 0
	v_pk_add_f32 v[190:191], v[110:111], v[114:115]
	s_waitcnt lgkmcnt(0)
	ds_read_b128 v[120:123], v77 offset:512
	ds_read_b128 v[124:127], v77 offset:528
	ds_read_b128 v[128:131], v77 offset:544
	ds_read_b128 v[132:135], v77 offset:560
	ds_read_b128 v[136:139], v77 offset:576
	ds_read_b128 v[140:143], v77 offset:592
	ds_read_b128 v[144:147], v77 offset:608
	ds_read_b128 v[148:151], v77 offset:624
	v_pk_fma_f32 v[110:111], v[152:153], v[2:3], v[78:79] op_sel:[0,0,1] op_sel_hi:[1,0,1]
	v_mul_f32_e64 v192, |v190|, s82
	v_pk_mul_f32 v[112:113], v[160:161], v[6:7] op_sel:[0,0] op_sel_hi:[1,0]
	v_mul_f32_e64 v193, |v191|, s82
	v_pk_mul_f32 v[114:115], v[168:169], v[10:11] op_sel:[0,0] op_sel_hi:[1,0]
	v_exp_f32_e32 v192, v192
	v_pk_mul_f32 v[116:117], v[176:177], v[14:15] op_sel:[0,0] op_sel_hi:[1,0]
	v_exp_f32_e32 v193, v193
	v_pk_fma_f32 v[110:111], v[154:155], v[2:3], v[110:111] op_sel:[0,1,0] op_sel_hi:[1,1,1]
	v_max_f32_e64 v194, -v190, 0
	v_pk_fma_f32 v[112:113], v[162:163], v[6:7], v[112:113] op_sel:[0,1,0] op_sel_hi:[1,1,1]
	v_max_f32_e64 v195, -v191, 0
	v_pk_fma_f32 v[114:115], v[170:171], v[10:11], v[114:115] op_sel:[0,1,0] op_sel_hi:[1,1,1]
	v_add_f32_e32 v192, 1.0, v192
	v_pk_fma_f32 v[116:117], v[178:179], v[14:15], v[116:117] op_sel:[0,1,0] op_sel_hi:[1,1,1]
	v_add_f32_e32 v193, 1.0, v193
	v_pk_fma_f32 v[110:111], v[156:157], v[4:5], v[110:111] op_sel:[0,0,0] op_sel_hi:[1,0,1]
	v_log_f32_e32 v192, v192
	v_pk_fma_f32 v[112:113], v[164:165], v[8:9], v[112:113] op_sel:[0,0,0] op_sel_hi:[1,0,1]
	v_log_f32_e32 v193, v193
	v_pk_fma_f32 v[114:115], v[172:173], v[12:13], v[114:115] op_sel:[0,0,0] op_sel_hi:[1,0,1]
	s_nop 0
	v_pk_fma_f32 v[116:117], v[180:181], v[16:17], v[116:117] op_sel:[0,0,0] op_sel_hi:[1,0,1]
	v_fmac_f32_e32 v194, 0x3f317218, v192
	v_pk_fma_f32 v[110:111], v[158:159], v[4:5], v[110:111] op_sel:[0,1,0] op_sel_hi:[1,1,1]
	v_fmac_f32_e32 v195, 0x3f317218, v193
	v_pk_fma_f32 v[112:113], v[166:167], v[8:9], v[112:113] op_sel:[0,1,0] op_sel_hi:[1,1,1]
	v_fmamk_f32 v80, v194, 0xbd800000, v81
	v_pk_fma_f32 v[114:115], v[174:175], v[12:13], v[114:115] op_sel:[0,1,0] op_sel_hi:[1,1,1]
	v_fmamk_f32 v82, v195, 0xbd800000, v80
	v_pk_fma_f32 v[116:117], v[182:183], v[16:17], v[116:117] op_sel:[0,1,0] op_sel_hi:[1,1,1]
	v_pk_add_f32 v[110:111], v[110:111], v[112:113]
	v_pk_add_f32 v[114:115], v[114:115], v[116:117]
	s_nop 0
	v_pk_add_f32 v[198:199], v[110:111], v[114:115]
	s_waitcnt lgkmcnt(0)
	ds_read_b128 v[152:155], v77 offset:640
	ds_read_b128 v[156:159], v77 offset:656
	ds_read_b128 v[160:163], v77 offset:672
	ds_read_b128 v[164:167], v77 offset:688
	ds_read_b128 v[168:171], v77 offset:704
	ds_read_b128 v[172:175], v77 offset:720
	ds_read_b128 v[176:179], v77 offset:736
	ds_read_b128 v[180:183], v77 offset:752
	v_pk_fma_f32 v[110:111], v[120:121], v[2:3], v[78:79] op_sel:[0,0,1] op_sel_hi:[1,0,1]
	v_mul_f32_e64 v200, |v198|, s82
	v_pk_mul_f32 v[112:113], v[128:129], v[6:7] op_sel:[0,0] op_sel_hi:[1,0]
	v_mul_f32_e64 v201, |v199|, s82
	v_pk_mul_f32 v[114:115], v[136:137], v[10:11] op_sel:[0,0] op_sel_hi:[1,0]
	v_exp_f32_e32 v200, v200
	v_pk_mul_f32 v[116:117], v[144:145], v[14:15] op_sel:[0,0] op_sel_hi:[1,0]
	v_exp_f32_e32 v201, v201
	v_pk_fma_f32 v[110:111], v[122:123], v[2:3], v[110:111] op_sel:[0,1,0] op_sel_hi:[1,1,1]
	v_max_f32_e64 v202, -v198, 0
	v_pk_fma_f32 v[112:113], v[130:131], v[6:7], v[112:113] op_sel:[0,1,0] op_sel_hi:[1,1,1]
	v_max_f32_e64 v203, -v199, 0
	v_pk_fma_f32 v[114:115], v[138:139], v[10:11], v[114:115] op_sel:[0,1,0] op_sel_hi:[1,1,1]
	v_add_f32_e32 v200, 1.0, v200
	v_pk_fma_f32 v[116:117], v[146:147], v[14:15], v[116:117] op_sel:[0,1,0] op_sel_hi:[1,1,1]
	v_add_f32_e32 v201, 1.0, v201
	v_pk_fma_f32 v[110:111], v[124:125], v[4:5], v[110:111] op_sel:[0,0,0] op_sel_hi:[1,0,1]
	v_log_f32_e32 v200, v200
	v_pk_fma_f32 v[112:113], v[132:133], v[8:9], v[112:113] op_sel:[0,0,0] op_sel_hi:[1,0,1]
	v_log_f32_e32 v201, v201
	v_pk_fma_f32 v[114:115], v[140:141], v[12:13], v[114:115] op_sel:[0,0,0] op_sel_hi:[1,0,1]
	s_nop 0
	v_pk_fma_f32 v[116:117], v[148:149], v[16:17], v[116:117] op_sel:[0,0,0] op_sel_hi:[1,0,1]
	v_fmac_f32_e32 v202, 0x3f317218, v200
	v_pk_fma_f32 v[110:111], v[126:127], v[4:5], v[110:111] op_sel:[0,1,0] op_sel_hi:[1,1,1]
	v_fmac_f32_e32 v203, 0x3f317218, v201
	v_pk_fma_f32 v[112:113], v[134:135], v[8:9], v[112:113] op_sel:[0,1,0] op_sel_hi:[1,1,1]
	v_fmamk_f32 v83, v202, 0xbd800000, v82
	v_pk_fma_f32 v[114:115], v[142:143], v[12:13], v[114:115] op_sel:[0,1,0] op_sel_hi:[1,1,1]
	v_fmamk_f32 v85, v203, 0xbd800000, v83
	v_pk_fma_f32 v[116:117], v[150:151], v[16:17], v[116:117] op_sel:[0,1,0] op_sel_hi:[1,1,1]
	v_pk_add_f32 v[110:111], v[110:111], v[112:113]
	v_pk_add_f32 v[114:115], v[114:115], v[116:117]
	s_nop 0
	v_pk_add_f32 v[190:191], v[110:111], v[114:115]
	s_waitcnt lgkmcnt(0)
	ds_read_b128 v[120:123], v77 offset:768
	ds_read_b128 v[124:127], v77 offset:784
	ds_read_b128 v[128:131], v77 offset:800
	ds_read_b128 v[132:135], v77 offset:816
	ds_read_b128 v[136:139], v77 offset:832
	ds_read_b128 v[140:143], v77 offset:848
	ds_read_b128 v[144:147], v77 offset:864
	ds_read_b128 v[148:151], v77 offset:880
	v_pk_fma_f32 v[110:111], v[152:153], v[2:3], v[78:79] op_sel:[0,0,1] op_sel_hi:[1,0,1]
	v_mul_f32_e64 v192, |v190|, s82
	v_pk_mul_f32 v[112:113], v[160:161], v[6:7] op_sel:[0,0] op_sel_hi:[1,0]
	v_mul_f32_e64 v193, |v191|, s82
	v_pk_mul_f32 v[114:115], v[168:169], v[10:11] op_sel:[0,0] op_sel_hi:[1,0]
	v_exp_f32_e32 v192, v192
	v_pk_mul_f32 v[116:117], v[176:177], v[14:15] op_sel:[0,0] op_sel_hi:[1,0]
	v_exp_f32_e32 v193, v193
	v_pk_fma_f32 v[110:111], v[154:155], v[2:3], v[110:111] op_sel:[0,1,0] op_sel_hi:[1,1,1]
	v_max_f32_e64 v194, -v190, 0
	v_pk_fma_f32 v[112:113], v[162:163], v[6:7], v[112:113] op_sel:[0,1,0] op_sel_hi:[1,1,1]
	v_max_f32_e64 v195, -v191, 0
	v_pk_fma_f32 v[114:115], v[170:171], v[10:11], v[114:115] op_sel:[0,1,0] op_sel_hi:[1,1,1]
	v_add_f32_e32 v192, 1.0, v192
	v_pk_fma_f32 v[116:117], v[178:179], v[14:15], v[116:117] op_sel:[0,1,0] op_sel_hi:[1,1,1]
	v_add_f32_e32 v193, 1.0, v193
	v_pk_fma_f32 v[110:111], v[156:157], v[4:5], v[110:111] op_sel:[0,0,0] op_sel_hi:[1,0,1]
	v_log_f32_e32 v192, v192
	v_pk_fma_f32 v[112:113], v[164:165], v[8:9], v[112:113] op_sel:[0,0,0] op_sel_hi:[1,0,1]
	v_log_f32_e32 v193, v193
	v_pk_fma_f32 v[114:115], v[172:173], v[12:13], v[114:115] op_sel:[0,0,0] op_sel_hi:[1,0,1]
	s_nop 0
	v_pk_fma_f32 v[116:117], v[180:181], v[16:17], v[116:117] op_sel:[0,0,0] op_sel_hi:[1,0,1]
	v_fmac_f32_e32 v194, 0x3f317218, v192
	v_pk_fma_f32 v[110:111], v[158:159], v[4:5], v[110:111] op_sel:[0,1,0] op_sel_hi:[1,1,1]
	v_fmac_f32_e32 v195, 0x3f317218, v193
	v_pk_fma_f32 v[112:113], v[166:167], v[8:9], v[112:113] op_sel:[0,1,0] op_sel_hi:[1,1,1]
	v_fmamk_f32 v84, v194, 0xbd800000, v85
	v_pk_fma_f32 v[114:115], v[174:175], v[12:13], v[114:115] op_sel:[0,1,0] op_sel_hi:[1,1,1]
	v_fmamk_f32 v87, v195, 0xbd800000, v84
	v_pk_fma_f32 v[116:117], v[182:183], v[16:17], v[116:117] op_sel:[0,1,0] op_sel_hi:[1,1,1]
	v_pk_add_f32 v[110:111], v[110:111], v[112:113]
	v_pk_add_f32 v[114:115], v[114:115], v[116:117]
	s_nop 0
	v_pk_add_f32 v[198:199], v[110:111], v[114:115]
	s_waitcnt lgkmcnt(0)
	ds_read_b128 v[152:155], v77 offset:896
	ds_read_b128 v[156:159], v77 offset:912
	ds_read_b128 v[160:163], v77 offset:928
	ds_read_b128 v[164:167], v77 offset:944
	ds_read_b128 v[168:171], v77 offset:960
	ds_read_b128 v[172:175], v77 offset:976
	ds_read_b128 v[176:179], v77 offset:992
	ds_read_b128 v[180:183], v77 offset:1008
	v_pk_fma_f32 v[110:111], v[120:121], v[2:3], v[78:79] op_sel:[0,0,1] op_sel_hi:[1,0,1]
	v_mul_f32_e64 v200, |v198|, s82
	v_pk_mul_f32 v[112:113], v[128:129], v[6:7] op_sel:[0,0] op_sel_hi:[1,0]
	v_mul_f32_e64 v201, |v199|, s82
	v_pk_mul_f32 v[114:115], v[136:137], v[10:11] op_sel:[0,0] op_sel_hi:[1,0]
	v_exp_f32_e32 v200, v200
	v_pk_mul_f32 v[116:117], v[144:145], v[14:15] op_sel:[0,0] op_sel_hi:[1,0]
	v_exp_f32_e32 v201, v201
	v_pk_fma_f32 v[110:111], v[122:123], v[2:3], v[110:111] op_sel:[0,1,0] op_sel_hi:[1,1,1]
	v_max_f32_e64 v202, -v198, 0
	v_pk_fma_f32 v[112:113], v[130:131], v[6:7], v[112:113] op_sel:[0,1,0] op_sel_hi:[1,1,1]
	v_max_f32_e64 v203, -v199, 0
	v_pk_fma_f32 v[114:115], v[138:139], v[10:11], v[114:115] op_sel:[0,1,0] op_sel_hi:[1,1,1]
	v_add_f32_e32 v200, 1.0, v200
	v_pk_fma_f32 v[116:117], v[146:147], v[14:15], v[116:117] op_sel:[0,1,0] op_sel_hi:[1,1,1]
	v_add_f32_e32 v201, 1.0, v201
	v_pk_fma_f32 v[110:111], v[124:125], v[4:5], v[110:111] op_sel:[0,0,0] op_sel_hi:[1,0,1]
	v_log_f32_e32 v200, v200
	v_pk_fma_f32 v[112:113], v[132:133], v[8:9], v[112:113] op_sel:[0,0,0] op_sel_hi:[1,0,1]
	v_log_f32_e32 v201, v201
	v_pk_fma_f32 v[114:115], v[140:141], v[12:13], v[114:115] op_sel:[0,0,0] op_sel_hi:[1,0,1]
	s_nop 0
	v_pk_fma_f32 v[116:117], v[148:149], v[16:17], v[116:117] op_sel:[0,0,0] op_sel_hi:[1,0,1]
	v_fmac_f32_e32 v202, 0x3f317218, v200
	v_pk_fma_f32 v[110:111], v[126:127], v[4:5], v[110:111] op_sel:[0,1,0] op_sel_hi:[1,1,1]
	v_fmac_f32_e32 v203, 0x3f317218, v201
	v_pk_fma_f32 v[112:113], v[134:135], v[8:9], v[112:113] op_sel:[0,1,0] op_sel_hi:[1,1,1]
	v_fmamk_f32 v88, v202, 0xbd800000, v87
	v_pk_fma_f32 v[114:115], v[142:143], v[12:13], v[114:115] op_sel:[0,1,0] op_sel_hi:[1,1,1]
	v_fmamk_f32 v90, v203, 0xbd800000, v88
	v_pk_fma_f32 v[116:117], v[150:151], v[16:17], v[116:117] op_sel:[0,1,0] op_sel_hi:[1,1,1]
	v_pk_add_f32 v[110:111], v[110:111], v[112:113]
	v_pk_add_f32 v[114:115], v[114:115], v[116:117]
	s_nop 0
	v_pk_add_f32 v[190:191], v[110:111], v[114:115]
	s_waitcnt lgkmcnt(0)
	ds_read_b128 v[120:123], v77 offset:1024
	ds_read_b128 v[124:127], v77 offset:1040
	ds_read_b128 v[128:131], v77 offset:1056
	ds_read_b128 v[132:135], v77 offset:1072
	ds_read_b128 v[136:139], v77 offset:1088
	ds_read_b128 v[140:143], v77 offset:1104
	ds_read_b128 v[144:147], v77 offset:1120
	ds_read_b128 v[148:151], v77 offset:1136
	v_pk_fma_f32 v[110:111], v[152:153], v[2:3], v[78:79] op_sel:[0,0,1] op_sel_hi:[1,0,1]
	v_mul_f32_e64 v192, |v190|, s82
	v_pk_mul_f32 v[112:113], v[160:161], v[6:7] op_sel:[0,0] op_sel_hi:[1,0]
	v_mul_f32_e64 v193, |v191|, s82
	v_pk_mul_f32 v[114:115], v[168:169], v[10:11] op_sel:[0,0] op_sel_hi:[1,0]
	v_exp_f32_e32 v192, v192
	v_pk_mul_f32 v[116:117], v[176:177], v[14:15] op_sel:[0,0] op_sel_hi:[1,0]
	v_exp_f32_e32 v193, v193
	v_pk_fma_f32 v[110:111], v[154:155], v[2:3], v[110:111] op_sel:[0,1,0] op_sel_hi:[1,1,1]
	v_max_f32_e64 v194, -v190, 0
	v_pk_fma_f32 v[112:113], v[162:163], v[6:7], v[112:113] op_sel:[0,1,0] op_sel_hi:[1,1,1]
	v_max_f32_e64 v195, -v191, 0
	v_pk_fma_f32 v[114:115], v[170:171], v[10:11], v[114:115] op_sel:[0,1,0] op_sel_hi:[1,1,1]
	v_add_f32_e32 v192, 1.0, v192
	v_pk_fma_f32 v[116:117], v[178:179], v[14:15], v[116:117] op_sel:[0,1,0] op_sel_hi:[1,1,1]
	v_add_f32_e32 v193, 1.0, v193
	v_pk_fma_f32 v[110:111], v[156:157], v[4:5], v[110:111] op_sel:[0,0,0] op_sel_hi:[1,0,1]
	v_log_f32_e32 v192, v192
	v_pk_fma_f32 v[112:113], v[164:165], v[8:9], v[112:113] op_sel:[0,0,0] op_sel_hi:[1,0,1]
	v_log_f32_e32 v193, v193
	v_pk_fma_f32 v[114:115], v[172:173], v[12:13], v[114:115] op_sel:[0,0,0] op_sel_hi:[1,0,1]
	s_nop 0
	v_pk_fma_f32 v[116:117], v[180:181], v[16:17], v[116:117] op_sel:[0,0,0] op_sel_hi:[1,0,1]
	v_fmac_f32_e32 v194, 0x3f317218, v192
	v_pk_fma_f32 v[110:111], v[158:159], v[4:5], v[110:111] op_sel:[0,1,0] op_sel_hi:[1,1,1]
	v_fmac_f32_e32 v195, 0x3f317218, v193
	v_pk_fma_f32 v[112:113], v[166:167], v[8:9], v[112:113] op_sel:[0,1,0] op_sel_hi:[1,1,1]
	v_fmamk_f32 v89, v194, 0xbd800000, v90
	v_pk_fma_f32 v[114:115], v[174:175], v[12:13], v[114:115] op_sel:[0,1,0] op_sel_hi:[1,1,1]
	v_fmamk_f32 v91, v195, 0xbd800000, v89
	v_pk_fma_f32 v[116:117], v[182:183], v[16:17], v[116:117] op_sel:[0,1,0] op_sel_hi:[1,1,1]
	v_pk_add_f32 v[110:111], v[110:111], v[112:113]
	v_pk_add_f32 v[114:115], v[114:115], v[116:117]
	s_nop 0
	v_pk_add_f32 v[198:199], v[110:111], v[114:115]
	s_waitcnt lgkmcnt(0)
	ds_read_b128 v[152:155], v77 offset:1152
	ds_read_b128 v[156:159], v77 offset:1168
	ds_read_b128 v[160:163], v77 offset:1184
	ds_read_b128 v[164:167], v77 offset:1200
	ds_read_b128 v[168:171], v77 offset:1216
	ds_read_b128 v[172:175], v77 offset:1232
	ds_read_b128 v[176:179], v77 offset:1248
	ds_read_b128 v[180:183], v77 offset:1264
	v_pk_fma_f32 v[110:111], v[120:121], v[2:3], v[78:79] op_sel:[0,0,1] op_sel_hi:[1,0,1]
	v_mul_f32_e64 v200, |v198|, s82
	v_pk_mul_f32 v[112:113], v[128:129], v[6:7] op_sel:[0,0] op_sel_hi:[1,0]
	v_mul_f32_e64 v201, |v199|, s82
	v_pk_mul_f32 v[114:115], v[136:137], v[10:11] op_sel:[0,0] op_sel_hi:[1,0]
	v_exp_f32_e32 v200, v200
	v_pk_mul_f32 v[116:117], v[144:145], v[14:15] op_sel:[0,0] op_sel_hi:[1,0]
	v_exp_f32_e32 v201, v201
	v_pk_fma_f32 v[110:111], v[122:123], v[2:3], v[110:111] op_sel:[0,1,0] op_sel_hi:[1,1,1]
	v_max_f32_e64 v202, -v198, 0
	v_pk_fma_f32 v[112:113], v[130:131], v[6:7], v[112:113] op_sel:[0,1,0] op_sel_hi:[1,1,1]
	v_max_f32_e64 v203, -v199, 0
	v_pk_fma_f32 v[114:115], v[138:139], v[10:11], v[114:115] op_sel:[0,1,0] op_sel_hi:[1,1,1]
	v_add_f32_e32 v200, 1.0, v200
	v_pk_fma_f32 v[116:117], v[146:147], v[14:15], v[116:117] op_sel:[0,1,0] op_sel_hi:[1,1,1]
	v_add_f32_e32 v201, 1.0, v201
	v_pk_fma_f32 v[110:111], v[124:125], v[4:5], v[110:111] op_sel:[0,0,0] op_sel_hi:[1,0,1]
	v_log_f32_e32 v200, v200
	v_pk_fma_f32 v[112:113], v[132:133], v[8:9], v[112:113] op_sel:[0,0,0] op_sel_hi:[1,0,1]
	v_log_f32_e32 v201, v201
	v_pk_fma_f32 v[114:115], v[140:141], v[12:13], v[114:115] op_sel:[0,0,0] op_sel_hi:[1,0,1]
	s_nop 0
	v_pk_fma_f32 v[116:117], v[148:149], v[16:17], v[116:117] op_sel:[0,0,0] op_sel_hi:[1,0,1]
	v_fmac_f32_e32 v202, 0x3f317218, v200
	v_pk_fma_f32 v[110:111], v[126:127], v[4:5], v[110:111] op_sel:[0,1,0] op_sel_hi:[1,1,1]
	v_fmac_f32_e32 v203, 0x3f317218, v201
	v_pk_fma_f32 v[112:113], v[134:135], v[8:9], v[112:113] op_sel:[0,1,0] op_sel_hi:[1,1,1]
	v_fmamk_f32 v92, v202, 0xbd800000, v91
	v_pk_fma_f32 v[114:115], v[142:143], v[12:13], v[114:115] op_sel:[0,1,0] op_sel_hi:[1,1,1]
	v_fmamk_f32 v94, v203, 0xbd800000, v92
	v_pk_fma_f32 v[116:117], v[150:151], v[16:17], v[116:117] op_sel:[0,1,0] op_sel_hi:[1,1,1]
	v_pk_add_f32 v[110:111], v[110:111], v[112:113]
	v_pk_add_f32 v[114:115], v[114:115], v[116:117]
	s_nop 0
	v_pk_add_f32 v[190:191], v[110:111], v[114:115]
	s_waitcnt lgkmcnt(0)
	ds_read_b128 v[120:123], v77 offset:1280
	ds_read_b128 v[124:127], v77 offset:1296
	ds_read_b128 v[128:131], v77 offset:1312
	ds_read_b128 v[132:135], v77 offset:1328
	ds_read_b128 v[136:139], v77 offset:1344
	ds_read_b128 v[140:143], v77 offset:1360
	ds_read_b128 v[144:147], v77 offset:1376
	ds_read_b128 v[148:151], v77 offset:1392
	v_pk_fma_f32 v[110:111], v[152:153], v[2:3], v[78:79] op_sel:[0,0,1] op_sel_hi:[1,0,1]
	v_mul_f32_e64 v192, |v190|, s82
	v_pk_mul_f32 v[112:113], v[160:161], v[6:7] op_sel:[0,0] op_sel_hi:[1,0]
	v_mul_f32_e64 v193, |v191|, s82
	v_pk_mul_f32 v[114:115], v[168:169], v[10:11] op_sel:[0,0] op_sel_hi:[1,0]
	v_exp_f32_e32 v192, v192
	v_pk_mul_f32 v[116:117], v[176:177], v[14:15] op_sel:[0,0] op_sel_hi:[1,0]
	v_exp_f32_e32 v193, v193
	v_pk_fma_f32 v[110:111], v[154:155], v[2:3], v[110:111] op_sel:[0,1,0] op_sel_hi:[1,1,1]
	v_max_f32_e64 v194, -v190, 0
	v_pk_fma_f32 v[112:113], v[162:163], v[6:7], v[112:113] op_sel:[0,1,0] op_sel_hi:[1,1,1]
	v_max_f32_e64 v195, -v191, 0
	v_pk_fma_f32 v[114:115], v[170:171], v[10:11], v[114:115] op_sel:[0,1,0] op_sel_hi:[1,1,1]
	v_add_f32_e32 v192, 1.0, v192
	v_pk_fma_f32 v[116:117], v[178:179], v[14:15], v[116:117] op_sel:[0,1,0] op_sel_hi:[1,1,1]
	v_add_f32_e32 v193, 1.0, v193
	v_pk_fma_f32 v[110:111], v[156:157], v[4:5], v[110:111] op_sel:[0,0,0] op_sel_hi:[1,0,1]
	v_log_f32_e32 v192, v192
	v_pk_fma_f32 v[112:113], v[164:165], v[8:9], v[112:113] op_sel:[0,0,0] op_sel_hi:[1,0,1]
	v_log_f32_e32 v193, v193
	v_pk_fma_f32 v[114:115], v[172:173], v[12:13], v[114:115] op_sel:[0,0,0] op_sel_hi:[1,0,1]
	s_nop 0
	v_pk_fma_f32 v[116:117], v[180:181], v[16:17], v[116:117] op_sel:[0,0,0] op_sel_hi:[1,0,1]
	v_fmac_f32_e32 v194, 0x3f317218, v192
	v_pk_fma_f32 v[110:111], v[158:159], v[4:5], v[110:111] op_sel:[0,1,0] op_sel_hi:[1,1,1]
	v_fmac_f32_e32 v195, 0x3f317218, v193
	v_pk_fma_f32 v[112:113], v[166:167], v[8:9], v[112:113] op_sel:[0,1,0] op_sel_hi:[1,1,1]
	v_fmamk_f32 v93, v194, 0xbd800000, v94
	v_pk_fma_f32 v[114:115], v[174:175], v[12:13], v[114:115] op_sel:[0,1,0] op_sel_hi:[1,1,1]
	v_fmamk_f32 v95, v195, 0xbd800000, v93
	v_pk_fma_f32 v[116:117], v[182:183], v[16:17], v[116:117] op_sel:[0,1,0] op_sel_hi:[1,1,1]
	v_pk_add_f32 v[110:111], v[110:111], v[112:113]
	v_pk_add_f32 v[114:115], v[114:115], v[116:117]
	s_nop 0
	v_pk_add_f32 v[198:199], v[110:111], v[114:115]
	s_waitcnt lgkmcnt(0)
	ds_read_b128 v[152:155], v77 offset:1408
	ds_read_b128 v[156:159], v77 offset:1424
	ds_read_b128 v[160:163], v77 offset:1440
	ds_read_b128 v[164:167], v77 offset:1456
	ds_read_b128 v[168:171], v77 offset:1472
	ds_read_b128 v[172:175], v77 offset:1488
	ds_read_b128 v[176:179], v77 offset:1504
	ds_read_b128 v[180:183], v77 offset:1520
	v_pk_fma_f32 v[110:111], v[120:121], v[2:3], v[78:79] op_sel:[0,0,1] op_sel_hi:[1,0,1]
	v_mul_f32_e64 v200, |v198|, s82
	v_pk_mul_f32 v[112:113], v[128:129], v[6:7] op_sel:[0,0] op_sel_hi:[1,0]
	v_mul_f32_e64 v201, |v199|, s82
	v_pk_mul_f32 v[114:115], v[136:137], v[10:11] op_sel:[0,0] op_sel_hi:[1,0]
	v_exp_f32_e32 v200, v200
	v_pk_mul_f32 v[116:117], v[144:145], v[14:15] op_sel:[0,0] op_sel_hi:[1,0]
	v_exp_f32_e32 v201, v201
	v_pk_fma_f32 v[110:111], v[122:123], v[2:3], v[110:111] op_sel:[0,1,0] op_sel_hi:[1,1,1]
	v_max_f32_e64 v202, -v198, 0
	v_pk_fma_f32 v[112:113], v[130:131], v[6:7], v[112:113] op_sel:[0,1,0] op_sel_hi:[1,1,1]
	v_max_f32_e64 v203, -v199, 0
	v_pk_fma_f32 v[114:115], v[138:139], v[10:11], v[114:115] op_sel:[0,1,0] op_sel_hi:[1,1,1]
	v_add_f32_e32 v200, 1.0, v200
	v_pk_fma_f32 v[116:117], v[146:147], v[14:15], v[116:117] op_sel:[0,1,0] op_sel_hi:[1,1,1]
	v_add_f32_e32 v201, 1.0, v201
	v_pk_fma_f32 v[110:111], v[124:125], v[4:5], v[110:111] op_sel:[0,0,0] op_sel_hi:[1,0,1]
	v_log_f32_e32 v200, v200
	v_pk_fma_f32 v[112:113], v[132:133], v[8:9], v[112:113] op_sel:[0,0,0] op_sel_hi:[1,0,1]
	v_log_f32_e32 v201, v201
	v_pk_fma_f32 v[114:115], v[140:141], v[12:13], v[114:115] op_sel:[0,0,0] op_sel_hi:[1,0,1]
	s_nop 0
	v_pk_fma_f32 v[116:117], v[148:149], v[16:17], v[116:117] op_sel:[0,0,0] op_sel_hi:[1,0,1]
	v_fmac_f32_e32 v202, 0x3f317218, v200
	v_pk_fma_f32 v[110:111], v[126:127], v[4:5], v[110:111] op_sel:[0,1,0] op_sel_hi:[1,1,1]
	v_fmac_f32_e32 v203, 0x3f317218, v201
	v_pk_fma_f32 v[112:113], v[134:135], v[8:9], v[112:113] op_sel:[0,1,0] op_sel_hi:[1,1,1]
	v_fmamk_f32 v96, v202, 0xbd800000, v95
	v_pk_fma_f32 v[114:115], v[142:143], v[12:13], v[114:115] op_sel:[0,1,0] op_sel_hi:[1,1,1]
	v_fmamk_f32 v98, v203, 0xbd800000, v96
	v_pk_fma_f32 v[116:117], v[150:151], v[16:17], v[116:117] op_sel:[0,1,0] op_sel_hi:[1,1,1]
	v_pk_add_f32 v[110:111], v[110:111], v[112:113]
	v_pk_add_f32 v[114:115], v[114:115], v[116:117]
	s_nop 0
	v_pk_add_f32 v[190:191], v[110:111], v[114:115]
	s_waitcnt lgkmcnt(0)
	ds_read_b128 v[120:123], v77 offset:1536
	ds_read_b128 v[124:127], v77 offset:1552
	ds_read_b128 v[128:131], v77 offset:1568
	ds_read_b128 v[132:135], v77 offset:1584
	ds_read_b128 v[136:139], v77 offset:1600
	ds_read_b128 v[140:143], v77 offset:1616
	ds_read_b128 v[144:147], v77 offset:1632
	ds_read_b128 v[148:151], v77 offset:1648
	v_pk_fma_f32 v[110:111], v[152:153], v[2:3], v[78:79] op_sel:[0,0,1] op_sel_hi:[1,0,1]
	v_mul_f32_e64 v192, |v190|, s82
	v_pk_mul_f32 v[112:113], v[160:161], v[6:7] op_sel:[0,0] op_sel_hi:[1,0]
	v_mul_f32_e64 v193, |v191|, s82
	v_pk_mul_f32 v[114:115], v[168:169], v[10:11] op_sel:[0,0] op_sel_hi:[1,0]
	v_exp_f32_e32 v192, v192
	v_pk_mul_f32 v[116:117], v[176:177], v[14:15] op_sel:[0,0] op_sel_hi:[1,0]
	v_exp_f32_e32 v193, v193
	v_pk_fma_f32 v[110:111], v[154:155], v[2:3], v[110:111] op_sel:[0,1,0] op_sel_hi:[1,1,1]
	v_max_f32_e64 v194, -v190, 0
	v_pk_fma_f32 v[112:113], v[162:163], v[6:7], v[112:113] op_sel:[0,1,0] op_sel_hi:[1,1,1]
	v_max_f32_e64 v195, -v191, 0
	v_pk_fma_f32 v[114:115], v[170:171], v[10:11], v[114:115] op_sel:[0,1,0] op_sel_hi:[1,1,1]
	v_add_f32_e32 v192, 1.0, v192
	v_pk_fma_f32 v[116:117], v[178:179], v[14:15], v[116:117] op_sel:[0,1,0] op_sel_hi:[1,1,1]
	v_add_f32_e32 v193, 1.0, v193
	v_pk_fma_f32 v[110:111], v[156:157], v[4:5], v[110:111] op_sel:[0,0,0] op_sel_hi:[1,0,1]
	v_log_f32_e32 v192, v192
	v_pk_fma_f32 v[112:113], v[164:165], v[8:9], v[112:113] op_sel:[0,0,0] op_sel_hi:[1,0,1]
	v_log_f32_e32 v193, v193
	v_pk_fma_f32 v[114:115], v[172:173], v[12:13], v[114:115] op_sel:[0,0,0] op_sel_hi:[1,0,1]
	s_nop 0
	v_pk_fma_f32 v[116:117], v[180:181], v[16:17], v[116:117] op_sel:[0,0,0] op_sel_hi:[1,0,1]
	v_fmac_f32_e32 v194, 0x3f317218, v192
	v_pk_fma_f32 v[110:111], v[158:159], v[4:5], v[110:111] op_sel:[0,1,0] op_sel_hi:[1,1,1]
	v_fmac_f32_e32 v195, 0x3f317218, v193
	v_pk_fma_f32 v[112:113], v[166:167], v[8:9], v[112:113] op_sel:[0,1,0] op_sel_hi:[1,1,1]
	v_fmamk_f32 v97, v194, 0xbd800000, v98
	v_pk_fma_f32 v[114:115], v[174:175], v[12:13], v[114:115] op_sel:[0,1,0] op_sel_hi:[1,1,1]
	v_fmamk_f32 v99, v195, 0xbd800000, v97
	v_pk_fma_f32 v[116:117], v[182:183], v[16:17], v[116:117] op_sel:[0,1,0] op_sel_hi:[1,1,1]
	v_pk_add_f32 v[110:111], v[110:111], v[112:113]
	v_pk_add_f32 v[114:115], v[114:115], v[116:117]
	s_nop 0
	v_pk_add_f32 v[198:199], v[110:111], v[114:115]
	s_waitcnt lgkmcnt(0)
	ds_read_b128 v[152:155], v77 offset:1664
	ds_read_b128 v[156:159], v77 offset:1680
	ds_read_b128 v[160:163], v77 offset:1696
	ds_read_b128 v[164:167], v77 offset:1712
	ds_read_b128 v[168:171], v77 offset:1728
	ds_read_b128 v[172:175], v77 offset:1744
	ds_read_b128 v[176:179], v77 offset:1760
	ds_read_b128 v[180:183], v77 offset:1776
	v_pk_fma_f32 v[110:111], v[120:121], v[2:3], v[78:79] op_sel:[0,0,1] op_sel_hi:[1,0,1]
	v_mul_f32_e64 v200, |v198|, s82
	v_pk_mul_f32 v[112:113], v[128:129], v[6:7] op_sel:[0,0] op_sel_hi:[1,0]
	v_mul_f32_e64 v201, |v199|, s82
	v_pk_mul_f32 v[114:115], v[136:137], v[10:11] op_sel:[0,0] op_sel_hi:[1,0]
	v_exp_f32_e32 v200, v200
	v_pk_mul_f32 v[116:117], v[144:145], v[14:15] op_sel:[0,0] op_sel_hi:[1,0]
	v_exp_f32_e32 v201, v201
	v_pk_fma_f32 v[110:111], v[122:123], v[2:3], v[110:111] op_sel:[0,1,0] op_sel_hi:[1,1,1]
	v_max_f32_e64 v202, -v198, 0
	v_pk_fma_f32 v[112:113], v[130:131], v[6:7], v[112:113] op_sel:[0,1,0] op_sel_hi:[1,1,1]
	v_max_f32_e64 v203, -v199, 0
	v_pk_fma_f32 v[114:115], v[138:139], v[10:11], v[114:115] op_sel:[0,1,0] op_sel_hi:[1,1,1]
	v_add_f32_e32 v200, 1.0, v200
	v_pk_fma_f32 v[116:117], v[146:147], v[14:15], v[116:117] op_sel:[0,1,0] op_sel_hi:[1,1,1]
	v_add_f32_e32 v201, 1.0, v201
	v_pk_fma_f32 v[110:111], v[124:125], v[4:5], v[110:111] op_sel:[0,0,0] op_sel_hi:[1,0,1]
	v_log_f32_e32 v200, v200
	v_pk_fma_f32 v[112:113], v[132:133], v[8:9], v[112:113] op_sel:[0,0,0] op_sel_hi:[1,0,1]
	v_log_f32_e32 v201, v201
	v_pk_fma_f32 v[114:115], v[140:141], v[12:13], v[114:115] op_sel:[0,0,0] op_sel_hi:[1,0,1]
	s_nop 0
	v_pk_fma_f32 v[116:117], v[148:149], v[16:17], v[116:117] op_sel:[0,0,0] op_sel_hi:[1,0,1]
	v_fmac_f32_e32 v202, 0x3f317218, v200
	v_pk_fma_f32 v[110:111], v[126:127], v[4:5], v[110:111] op_sel:[0,1,0] op_sel_hi:[1,1,1]
	v_fmac_f32_e32 v203, 0x3f317218, v201
	v_pk_fma_f32 v[112:113], v[134:135], v[8:9], v[112:113] op_sel:[0,1,0] op_sel_hi:[1,1,1]
	v_fmamk_f32 v100, v202, 0xbd800000, v99
	v_pk_fma_f32 v[114:115], v[142:143], v[12:13], v[114:115] op_sel:[0,1,0] op_sel_hi:[1,1,1]
	v_fmamk_f32 v102, v203, 0xbd800000, v100
	v_pk_fma_f32 v[116:117], v[150:151], v[16:17], v[116:117] op_sel:[0,1,0] op_sel_hi:[1,1,1]
	v_pk_add_f32 v[110:111], v[110:111], v[112:113]
	v_pk_add_f32 v[114:115], v[114:115], v[116:117]
	s_nop 0
	v_pk_add_f32 v[190:191], v[110:111], v[114:115]
	s_waitcnt lgkmcnt(0)
	ds_read_b128 v[120:123], v77 offset:1792
	ds_read_b128 v[124:127], v77 offset:1808
	ds_read_b128 v[128:131], v77 offset:1824
	ds_read_b128 v[132:135], v77 offset:1840
	ds_read_b128 v[136:139], v77 offset:1856
	ds_read_b128 v[140:143], v77 offset:1872
	ds_read_b128 v[144:147], v77 offset:1888
	ds_read_b128 v[148:151], v77 offset:1904
	v_pk_fma_f32 v[110:111], v[152:153], v[2:3], v[78:79] op_sel:[0,0,1] op_sel_hi:[1,0,1]
	v_mul_f32_e64 v192, |v190|, s82
	v_pk_mul_f32 v[112:113], v[160:161], v[6:7] op_sel:[0,0] op_sel_hi:[1,0]
	v_mul_f32_e64 v193, |v191|, s82
	v_pk_mul_f32 v[114:115], v[168:169], v[10:11] op_sel:[0,0] op_sel_hi:[1,0]
	v_exp_f32_e32 v192, v192
	v_pk_mul_f32 v[116:117], v[176:177], v[14:15] op_sel:[0,0] op_sel_hi:[1,0]
	v_exp_f32_e32 v193, v193
	v_pk_fma_f32 v[110:111], v[154:155], v[2:3], v[110:111] op_sel:[0,1,0] op_sel_hi:[1,1,1]
	v_max_f32_e64 v194, -v190, 0
	v_pk_fma_f32 v[112:113], v[162:163], v[6:7], v[112:113] op_sel:[0,1,0] op_sel_hi:[1,1,1]
	v_max_f32_e64 v195, -v191, 0
	v_pk_fma_f32 v[114:115], v[170:171], v[10:11], v[114:115] op_sel:[0,1,0] op_sel_hi:[1,1,1]
	v_add_f32_e32 v192, 1.0, v192
	v_pk_fma_f32 v[116:117], v[178:179], v[14:15], v[116:117] op_sel:[0,1,0] op_sel_hi:[1,1,1]
	v_add_f32_e32 v193, 1.0, v193
	v_pk_fma_f32 v[110:111], v[156:157], v[4:5], v[110:111] op_sel:[0,0,0] op_sel_hi:[1,0,1]
	v_log_f32_e32 v192, v192
	v_pk_fma_f32 v[112:113], v[164:165], v[8:9], v[112:113] op_sel:[0,0,0] op_sel_hi:[1,0,1]
	v_log_f32_e32 v193, v193
	v_pk_fma_f32 v[114:115], v[172:173], v[12:13], v[114:115] op_sel:[0,0,0] op_sel_hi:[1,0,1]
	s_nop 0
	v_pk_fma_f32 v[116:117], v[180:181], v[16:17], v[116:117] op_sel:[0,0,0] op_sel_hi:[1,0,1]
	v_fmac_f32_e32 v194, 0x3f317218, v192
	v_pk_fma_f32 v[110:111], v[158:159], v[4:5], v[110:111] op_sel:[0,1,0] op_sel_hi:[1,1,1]
	v_fmac_f32_e32 v195, 0x3f317218, v193
	v_pk_fma_f32 v[112:113], v[166:167], v[8:9], v[112:113] op_sel:[0,1,0] op_sel_hi:[1,1,1]
	v_fmamk_f32 v101, v194, 0xbd800000, v102
	v_pk_fma_f32 v[114:115], v[174:175], v[12:13], v[114:115] op_sel:[0,1,0] op_sel_hi:[1,1,1]
	v_fmamk_f32 v103, v195, 0xbd800000, v101
	v_pk_fma_f32 v[116:117], v[182:183], v[16:17], v[116:117] op_sel:[0,1,0] op_sel_hi:[1,1,1]
	v_pk_add_f32 v[110:111], v[110:111], v[112:113]
	v_pk_add_f32 v[114:115], v[114:115], v[116:117]
	s_nop 0
	v_pk_add_f32 v[198:199], v[110:111], v[114:115]
	s_waitcnt lgkmcnt(0)
	ds_read_b128 v[152:155], v77 offset:1920
	ds_read_b128 v[156:159], v77 offset:1936
	ds_read_b128 v[160:163], v77 offset:1952
	ds_read_b128 v[164:167], v77 offset:1968
	ds_read_b128 v[168:171], v77 offset:1984
	ds_read_b128 v[172:175], v77 offset:2000
	ds_read_b128 v[176:179], v77 offset:2016
	ds_read_b128 v[180:183], v77 offset:2032
	v_pk_fma_f32 v[110:111], v[120:121], v[2:3], v[78:79] op_sel:[0,0,1] op_sel_hi:[1,0,1]
	v_mul_f32_e64 v200, |v198|, s82
	v_pk_mul_f32 v[112:113], v[128:129], v[6:7] op_sel:[0,0] op_sel_hi:[1,0]
	v_mul_f32_e64 v201, |v199|, s82
	v_pk_mul_f32 v[114:115], v[136:137], v[10:11] op_sel:[0,0] op_sel_hi:[1,0]
	v_exp_f32_e32 v200, v200
	v_pk_mul_f32 v[116:117], v[144:145], v[14:15] op_sel:[0,0] op_sel_hi:[1,0]
	v_exp_f32_e32 v201, v201
	v_pk_fma_f32 v[110:111], v[122:123], v[2:3], v[110:111] op_sel:[0,1,0] op_sel_hi:[1,1,1]
	v_max_f32_e64 v202, -v198, 0
	v_pk_fma_f32 v[112:113], v[130:131], v[6:7], v[112:113] op_sel:[0,1,0] op_sel_hi:[1,1,1]
	v_max_f32_e64 v203, -v199, 0
	v_pk_fma_f32 v[114:115], v[138:139], v[10:11], v[114:115] op_sel:[0,1,0] op_sel_hi:[1,1,1]
	v_add_f32_e32 v200, 1.0, v200
	v_pk_fma_f32 v[116:117], v[146:147], v[14:15], v[116:117] op_sel:[0,1,0] op_sel_hi:[1,1,1]
	v_add_f32_e32 v201, 1.0, v201
	v_pk_fma_f32 v[110:111], v[124:125], v[4:5], v[110:111] op_sel:[0,0,0] op_sel_hi:[1,0,1]
	v_log_f32_e32 v200, v200
	v_pk_fma_f32 v[112:113], v[132:133], v[8:9], v[112:113] op_sel:[0,0,0] op_sel_hi:[1,0,1]
	v_log_f32_e32 v201, v201
	v_pk_fma_f32 v[114:115], v[140:141], v[12:13], v[114:115] op_sel:[0,0,0] op_sel_hi:[1,0,1]
	s_nop 0
	v_pk_fma_f32 v[116:117], v[148:149], v[16:17], v[116:117] op_sel:[0,0,0] op_sel_hi:[1,0,1]
	v_fmac_f32_e32 v202, 0x3f317218, v200
	v_pk_fma_f32 v[110:111], v[126:127], v[4:5], v[110:111] op_sel:[0,1,0] op_sel_hi:[1,1,1]
	v_fmac_f32_e32 v203, 0x3f317218, v201
	v_pk_fma_f32 v[112:113], v[134:135], v[8:9], v[112:113] op_sel:[0,1,0] op_sel_hi:[1,1,1]
	v_fmamk_f32 v104, v202, 0xbd800000, v103
	v_pk_fma_f32 v[114:115], v[142:143], v[12:13], v[114:115] op_sel:[0,1,0] op_sel_hi:[1,1,1]
	v_fmamk_f32 v107, v203, 0xbd800000, v104
	v_pk_fma_f32 v[116:117], v[150:151], v[16:17], v[116:117] op_sel:[0,1,0] op_sel_hi:[1,1,1]
	v_pk_add_f32 v[110:111], v[110:111], v[112:113]
	v_pk_add_f32 v[114:115], v[114:115], v[116:117]
	s_nop 0
	v_pk_add_f32 v[190:191], v[110:111], v[114:115]
	s_waitcnt lgkmcnt(0)
	v_pk_fma_f32 v[110:111], v[152:153], v[2:3], v[78:79] op_sel:[0,0,1] op_sel_hi:[1,0,1]
	v_mul_f32_e64 v192, |v190|, s82
	v_pk_mul_f32 v[112:113], v[160:161], v[6:7] op_sel:[0,0] op_sel_hi:[1,0]
	v_mul_f32_e64 v193, |v191|, s82
	v_pk_mul_f32 v[114:115], v[168:169], v[10:11] op_sel:[0,0] op_sel_hi:[1,0]
	v_exp_f32_e32 v192, v192
	v_pk_mul_f32 v[116:117], v[176:177], v[14:15] op_sel:[0,0] op_sel_hi:[1,0]
	v_exp_f32_e32 v193, v193
	v_pk_fma_f32 v[110:111], v[154:155], v[2:3], v[110:111] op_sel:[0,1,0] op_sel_hi:[1,1,1]
	v_max_f32_e64 v194, -v190, 0
	v_pk_fma_f32 v[112:113], v[162:163], v[6:7], v[112:113] op_sel:[0,1,0] op_sel_hi:[1,1,1]
	v_max_f32_e64 v195, -v191, 0
	v_pk_fma_f32 v[114:115], v[170:171], v[10:11], v[114:115] op_sel:[0,1,0] op_sel_hi:[1,1,1]
	v_add_f32_e32 v192, 1.0, v192
	v_pk_fma_f32 v[116:117], v[178:179], v[14:15], v[116:117] op_sel:[0,1,0] op_sel_hi:[1,1,1]
	v_add_f32_e32 v193, 1.0, v193
	v_pk_fma_f32 v[110:111], v[156:157], v[4:5], v[110:111] op_sel:[0,0,0] op_sel_hi:[1,0,1]
	v_log_f32_e32 v192, v192
	v_pk_fma_f32 v[112:113], v[164:165], v[8:9], v[112:113] op_sel:[0,0,0] op_sel_hi:[1,0,1]
	v_log_f32_e32 v193, v193
	v_pk_fma_f32 v[114:115], v[172:173], v[12:13], v[114:115] op_sel:[0,0,0] op_sel_hi:[1,0,1]
	s_nop 0
	v_pk_fma_f32 v[116:117], v[180:181], v[16:17], v[116:117] op_sel:[0,0,0] op_sel_hi:[1,0,1]
	v_fmac_f32_e32 v194, 0x3f317218, v192
	v_pk_fma_f32 v[110:111], v[158:159], v[4:5], v[110:111] op_sel:[0,1,0] op_sel_hi:[1,1,1]
	v_fmac_f32_e32 v195, 0x3f317218, v193
	v_pk_fma_f32 v[112:113], v[166:167], v[8:9], v[112:113] op_sel:[0,1,0] op_sel_hi:[1,1,1]
	v_fmamk_f32 v106, v194, 0xbd800000, v107
	v_pk_fma_f32 v[114:115], v[174:175], v[12:13], v[114:115] op_sel:[0,1,0] op_sel_hi:[1,1,1]
	v_fmamk_f32 v105, v195, 0xbd800000, v106
	v_pk_fma_f32 v[116:117], v[182:183], v[16:17], v[116:117] op_sel:[0,1,0] op_sel_hi:[1,1,1]
	v_pk_add_f32 v[110:111], v[110:111], v[112:113]
	v_pk_add_f32 v[114:115], v[114:115], v[116:117]
	s_nop 0
	v_pk_add_f32 v[198:199], v[110:111], v[114:115]
	v_mul_f32_e64 v200, |v198|, s82
	v_mul_f32_e64 v201, |v199|, s82
	v_exp_f32_e32 v200, v200
	v_exp_f32_e32 v201, v201
	v_max_f32_e64 v202, -v198, 0
	v_max_f32_e64 v203, -v199, 0
	v_add_f32_e32 v200, 1.0, v200
	v_add_f32_e32 v201, 1.0, v201
	v_log_f32_e32 v200, v200
	v_log_f32_e32 v201, v201
	s_nop 0
	v_fmac_f32_e32 v202, 0x3f317218, v200
	v_fmac_f32_e32 v203, 0x3f317218, v201
	v_fmamk_f32 v109, v202, 0xbd800000, v105
	v_fmamk_f32 v108, v203, 0xbd800000, v109
	ds_write_b32 v78, v108
	s_waitcnt vmcnt(7)
	ds_write_b128 v54, v[18:21]
	s_waitcnt vmcnt(6)
	ds_write_b128 v54, v[22:25] offset:33792
	s_waitcnt vmcnt(5)
	ds_write_b128 v56, v[26:29]
	s_waitcnt vmcnt(4)
	ds_write_b128 v56, v[30:33] offset:33792
	s_waitcnt vmcnt(3)
	ds_write_b128 v58, v[34:37]
	s_waitcnt vmcnt(2)
	ds_write_b128 v58, v[38:41] offset:33792
	s_waitcnt vmcnt(1)
	ds_write_b128 v60, v[42:45]
	s_waitcnt vmcnt(0)
	ds_write_b128 v60, v[46:49] offset:33792
	s_waitcnt lgkmcnt(0)
	s_barrier
	ds_read_b32 v18, v57
	ds_read_u16 v20, v59 offset:33792
	ds_read_u16 v21, v59 offset:34320
	ds_read_u16 v22, v59 offset:34848
	ds_read_u16 v23, v59 offset:35376
	ds_read_u16 v24, v59 offset:35904
	ds_read_u16 v25, v59 offset:36432
	ds_read_u16 v26, v59 offset:36960
	s_waitcnt lgkmcnt(7)
	v_cndmask_b32_e64 v19, v18, 0, s[4:5]
	v_add_f32_e32 v27, v86, v19
	v_mul_f32_e32 v36, 0x3fb8aa3b, v27
	v_mul_f32_e32 v27, 0xbfb8aa3b, v27
	v_exp_f32_e32 v27, v27
	s_waitcnt lgkmcnt(6)
	v_lshlrev_b32_e32 v20, 16, v20
	v_add_f32_e32 v0, v0, v19
	s_waitcnt lgkmcnt(5)
	v_lshlrev_b32_e32 v21, 16, v21
	v_mul_f32_e32 v20, v27, v20
	v_mul_f32_e32 v27, 0x3fb8aa3b, v0
	v_mul_f32_e32 v0, 0xbfb8aa3b, v0
	v_exp_f32_e32 v0, v0
	ds_read_u16 v28, v59
	ds_read_u16 v29, v59 offset:528
	ds_read_u16 v30, v59 offset:1056
	ds_read_u16 v31, v59 offset:1584
	ds_read_u16 v32, v59 offset:2112
	ds_read_u16 v33, v59 offset:2640
	ds_read_u16 v34, v59 offset:3168
	ds_read_u16 v35, v59 offset:50160
	v_exp_f32_e32 v27, v27
	v_cvt_pk_bf16_f32 v20, v20, s0
	v_mul_f32_e32 v0, v0, v21
	v_cvt_pk_bf16_f32 v0, v0, s0
	ds_write_b16 v59, v0 offset:34320
	v_add_f32_e32 v0, v69, v19
	s_waitcnt lgkmcnt(13)
	v_lshlrev_b32_e32 v21, 16, v22
	v_mul_f32_e32 v22, 0x3fb8aa3b, v0
	v_mul_f32_e32 v0, 0xbfb8aa3b, v0
	v_exp_f32_e32 v0, v0
	ds_write_b16 v59, v20 offset:33792
	s_waitcnt lgkmcnt(8)
	v_lshlrev_b32_e32 v20, 16, v29
	v_mul_f32_e32 v20, 0x3d800000, v20
	v_mul_f32_e32 v20, v27, v20
	v_exp_f32_e32 v22, v22
	v_cvt_pk_bf16_f32 v20, v20, s0
	v_mul_f32_e32 v0, v0, v21
	ds_write_b16 v59, v20 offset:528
	s_waitcnt lgkmcnt(8)
	v_lshlrev_b32_e32 v20, 16, v30
	v_cvt_pk_bf16_f32 v0, v0, s0
	v_mul_f32_e32 v20, 0x3d800000, v20
	ds_write_b16 v59, v0 offset:34848
	v_add_f32_e32 v0, v81, v19
	v_mul_f32_e32 v20, v22, v20
	v_mul_f32_e32 v22, 0x3fb8aa3b, v0
	v_mul_f32_e32 v0, 0xbfb8aa3b, v0
	v_exp_f32_e32 v0, v0
	v_lshlrev_b32_e32 v21, 16, v23
	v_exp_f32_e32 v22, v22
	v_cvt_pk_bf16_f32 v20, v20, s0
	v_mul_f32_e32 v0, v0, v21
	ds_write_b16 v59, v20 offset:1056
	s_waitcnt lgkmcnt(9)
	v_lshlrev_b32_e32 v20, 16, v31
	v_cvt_pk_bf16_f32 v0, v0, s0
	v_mul_f32_e32 v20, 0x3d800000, v20
	ds_write_b16 v59, v0 offset:35376
	v_add_f32_e32 v0, v80, v19
	v_mul_f32_e32 v20, v22, v20
	v_mul_f32_e32 v22, 0x3fb8aa3b, v0
	v_mul_f32_e32 v0, 0xbfb8aa3b, v0
	v_exp_f32_e32 v0, v0
	v_lshlrev_b32_e32 v21, 16, v24
	v_exp_f32_e32 v22, v22
	v_cvt_pk_bf16_f32 v20, v20, s0
	v_mul_f32_e32 v0, v0, v21
	ds_write_b16 v59, v20 offset:1584
	s_waitcnt lgkmcnt(10)
	v_lshlrev_b32_e32 v20, 16, v32
	v_cvt_pk_bf16_f32 v0, v0, s0
	v_mul_f32_e32 v20, 0x3d800000, v20
	ds_write_b16 v59, v0 offset:35904
	v_add_f32_e32 v0, v82, v19
	v_mul_f32_e32 v20, v22, v20
	v_mul_f32_e32 v22, 0x3fb8aa3b, v0
	v_mul_f32_e32 v0, 0xbfb8aa3b, v0
	v_exp_f32_e32 v0, v0
	v_lshlrev_b32_e32 v21, 16, v25
	v_exp_f32_e32 v22, v22
	v_cvt_pk_bf16_f32 v20, v20, s0
	v_mul_f32_e32 v0, v0, v21
	ds_write_b16 v59, v20 offset:2112
	s_waitcnt lgkmcnt(11)
	v_lshlrev_b32_e32 v20, 16, v33
	v_cvt_pk_bf16_f32 v0, v0, s0
	v_mul_f32_e32 v20, 0x3d800000, v20
	ds_write_b16 v59, v0 offset:36432
	v_add_f32_e32 v0, v83, v19
	v_mul_f32_e32 v20, v22, v20
	v_mul_f32_e32 v22, 0x3fb8aa3b, v0
	v_mul_f32_e32 v0, 0xbfb8aa3b, v0
	v_exp_f32_e32 v0, v0
	v_exp_f32_e32 v36, v36
	v_lshlrev_b32_e32 v21, 16, v26
	v_exp_f32_e32 v22, v22
	v_cvt_pk_bf16_f32 v20, v20, s0
	v_mul_f32_e32 v0, v0, v21
	v_lshlrev_b32_e32 v28, 16, v28
	ds_write_b16 v59, v20 offset:2640
	s_waitcnt lgkmcnt(12)
	v_lshlrev_b32_e32 v20, 16, v34
	v_cvt_pk_bf16_f32 v0, v0, s0
	v_mul_f32_e32 v28, 0x3d800000, v28
	v_mul_f32_e32 v20, 0x3d800000, v20
	ds_write_b16 v59, v0 offset:36960
	v_add_f32_e32 v0, v85, v19
	v_mul_f32_e32 v28, v36, v28
	v_mul_f32_e32 v20, v22, v20
	v_mul_f32_e32 v37, 0x3fb8aa3b, v0
	v_mul_f32_e32 v0, 0xbfb8aa3b, v0
	v_cvt_pk_bf16_f32 v28, v28, s0
	v_cvt_pk_bf16_f32 v20, v20, s0
	v_exp_f32_e32 v0, v0
	ds_write_b16 v59, v28
	ds_write_b16 v59, v20 offset:3168
	ds_read_u16 v20, v59 offset:3696
	ds_read_u16 v21, v59 offset:4224
	ds_read_u16 v22, v59 offset:4752
	ds_read_u16 v23, v59 offset:5280
	ds_read_u16 v24, v59 offset:5808
	ds_read_u16 v25, v59 offset:6336
	ds_read_u16 v26, v59 offset:6864
	ds_read_u16 v27, v59 offset:7392
	ds_read_u16 v28, v59 offset:37488
	ds_read_u16 v29, v59 offset:38016
	ds_read_u16 v30, v59 offset:38544
	ds_read_u16 v31, v59 offset:39072
	ds_read_u16 v32, v59 offset:39600
	ds_read_u16 v33, v59 offset:40128
	ds_read_u16 v34, v59 offset:40656
	ds_read_u16 v36, v59 offset:41184
	s_waitcnt lgkmcnt(7)
	v_lshlrev_b32_e32 v28, 16, v28
	v_mul_f32_e32 v0, v0, v28
	v_exp_f32_e32 v37, v37
	v_cvt_pk_bf16_f32 v0, v0, s0
	ds_write_b16 v59, v0 offset:37488
	v_add_f32_e32 v0, v84, v19
	v_lshlrev_b32_e32 v20, 16, v20
	v_mul_f32_e32 v28, 0x3fb8aa3b, v0
	v_mul_f32_e32 v0, 0xbfb8aa3b, v0
	v_mul_f32_e32 v20, 0x3d800000, v20
	v_exp_f32_e32 v0, v0
	v_mul_f32_e32 v20, v37, v20
	v_exp_f32_e32 v28, v28
	v_cvt_pk_bf16_f32 v20, v20, s0
	ds_write_b16 v59, v20 offset:3696
	v_lshlrev_b32_e32 v20, 16, v21
	s_waitcnt lgkmcnt(8)
	v_lshlrev_b32_e32 v21, 16, v29
	v_mul_f32_e32 v20, 0x3d800000, v20
	v_mul_f32_e32 v0, v0, v21
	v_mul_f32_e32 v20, v28, v20
	v_cvt_pk_bf16_f32 v0, v0, s0
	v_cvt_pk_bf16_f32 v20, v20, s0
	ds_write_b16 v59, v0 offset:38016
	v_add_f32_e32 v0, v87, v19
	ds_write_b16 v59, v20 offset:4224
	v_lshlrev_b32_e32 v20, 16, v22
	v_mul_f32_e32 v22, 0x3fb8aa3b, v0
	v_mul_f32_e32 v0, 0xbfb8aa3b, v0
	v_exp_f32_e32 v0, v0
	s_waitcnt lgkmcnt(9)
	v_lshlrev_b32_e32 v21, 16, v30
	v_exp_f32_e32 v22, v22
	v_mul_f32_e32 v20, 0x3d800000, v20
	v_mul_f32_e32 v0, v0, v21
	v_cvt_pk_bf16_f32 v0, v0, s0
	ds_write_b16 v59, v0 offset:38544
	v_add_f32_e32 v0, v88, v19
	v_mul_f32_e32 v20, v22, v20
	v_mul_f32_e32 v22, 0x3fb8aa3b, v0
	v_mul_f32_e32 v0, 0xbfb8aa3b, v0
	v_exp_f32_e32 v0, v0
	s_waitcnt lgkmcnt(9)
	v_lshlrev_b32_e32 v21, 16, v31
	v_exp_f32_e32 v22, v22
	v_cvt_pk_bf16_f32 v20, v20, s0
	v_mul_f32_e32 v0, v0, v21
	ds_write_b16 v59, v20 offset:4752
	v_lshlrev_b32_e32 v20, 16, v23
	v_cvt_pk_bf16_f32 v0, v0, s0
	v_mul_f32_e32 v20, 0x3d800000, v20
	ds_write_b16 v59, v0 offset:39072
	v_add_f32_e32 v0, v90, v19
	v_mul_f32_e32 v20, v22, v20
	v_mul_f32_e32 v22, 0x3fb8aa3b, v0
	v_mul_f32_e32 v0, 0xbfb8aa3b, v0
	v_exp_f32_e32 v0, v0
	s_waitcnt lgkmcnt(10)
	v_lshlrev_b32_e32 v21, 16, v32
	v_exp_f32_e32 v22, v22
	v_cvt_pk_bf16_f32 v20, v20, s0
	v_mul_f32_e32 v0, v0, v21
	ds_write_b16 v59, v20 offset:5280
	v_lshlrev_b32_e32 v20, 16, v24
	v_cvt_pk_bf16_f32 v0, v0, s0
	v_mul_f32_e32 v20, 0x3d800000, v20
	ds_write_b16 v59, v0 offset:39600
	v_add_f32_e32 v0, v89, v19
	v_mul_f32_e32 v20, v22, v20
	v_mul_f32_e32 v22, 0x3fb8aa3b, v0
	v_mul_f32_e32 v0, 0xbfb8aa3b, v0
	v_exp_f32_e32 v0, v0
	s_waitcnt lgkmcnt(11)
	v_lshlrev_b32_e32 v21, 16, v33
	v_exp_f32_e32 v22, v22
	v_cvt_pk_bf16_f32 v20, v20, s0
	v_mul_f32_e32 v0, v0, v21
	ds_write_b16 v59, v20 offset:5808
	v_lshlrev_b32_e32 v20, 16, v25
	v_cvt_pk_bf16_f32 v0, v0, s0
	v_mul_f32_e32 v20, 0x3d800000, v20
	ds_write_b16 v59, v0 offset:40128
	v_add_f32_e32 v0, v91, v19
	v_mul_f32_e32 v20, v22, v20
	v_mul_f32_e32 v22, 0x3fb8aa3b, v0
	v_mul_f32_e32 v0, 0xbfb8aa3b, v0
	v_exp_f32_e32 v0, v0
	s_waitcnt lgkmcnt(12)
	v_lshlrev_b32_e32 v21, 16, v34
	v_exp_f32_e32 v22, v22
	v_cvt_pk_bf16_f32 v20, v20, s0
	v_mul_f32_e32 v0, v0, v21
	ds_write_b16 v59, v20 offset:6336
	v_lshlrev_b32_e32 v20, 16, v26
	v_cvt_pk_bf16_f32 v0, v0, s0
	v_mul_f32_e32 v20, 0x3d800000, v20
	ds_write_b16 v59, v0 offset:40656
	v_add_f32_e32 v0, v92, v19
	v_mul_f32_e32 v20, v22, v20
	v_mul_f32_e32 v22, 0x3fb8aa3b, v0
	v_mul_f32_e32 v0, 0xbfb8aa3b, v0
	v_exp_f32_e32 v0, v0
	s_waitcnt lgkmcnt(13)
	v_lshlrev_b32_e32 v21, 16, v36
	v_exp_f32_e32 v22, v22
	v_cvt_pk_bf16_f32 v20, v20, s0
	v_mul_f32_e32 v0, v0, v21
	ds_write_b16 v59, v20 offset:6864
	v_lshlrev_b32_e32 v20, 16, v27
	v_cvt_pk_bf16_f32 v0, v0, s0
	v_mul_f32_e32 v20, 0x3d800000, v20
	ds_write_b16 v59, v0 offset:41184
	v_add_f32_e32 v0, v94, v19
	v_mul_f32_e32 v20, v22, v20
	v_mul_f32_e32 v37, 0x3fb8aa3b, v0
	v_mul_f32_e32 v0, 0xbfb8aa3b, v0
	v_cvt_pk_bf16_f32 v20, v20, s0
	v_exp_f32_e32 v0, v0
	ds_write_b16 v59, v20 offset:7392
	ds_read_u16 v20, v59 offset:7920
	ds_read_u16 v21, v59 offset:8448
	ds_read_u16 v22, v59 offset:8976
	ds_read_u16 v23, v59 offset:9504
	ds_read_u16 v24, v59 offset:10032
	ds_read_u16 v25, v59 offset:10560
	ds_read_u16 v26, v59 offset:11088
	ds_read_u16 v27, v59 offset:11616
	ds_read_u16 v28, v59 offset:41712
	ds_read_u16 v29, v59 offset:42240
	ds_read_u16 v30, v59 offset:42768
	ds_read_u16 v31, v59 offset:43296
	ds_read_u16 v32, v59 offset:43824
	ds_read_u16 v33, v59 offset:44352
	ds_read_u16 v34, v59 offset:44880
	ds_read_u16 v36, v59 offset:45408
	s_waitcnt lgkmcnt(7)
	v_lshlrev_b32_e32 v28, 16, v28
	v_mul_f32_e32 v0, v0, v28
	v_exp_f32_e32 v37, v37
	v_cvt_pk_bf16_f32 v0, v0, s0
	ds_write_b16 v59, v0 offset:41712
	v_add_f32_e32 v0, v93, v19
	v_lshlrev_b32_e32 v20, 16, v20
	v_mul_f32_e32 v28, 0x3fb8aa3b, v0
	v_mul_f32_e32 v0, 0xbfb8aa3b, v0
	v_mul_f32_e32 v20, 0x3d800000, v20
	v_exp_f32_e32 v0, v0
	v_mul_f32_e32 v20, v37, v20
	v_exp_f32_e32 v28, v28
	v_cvt_pk_bf16_f32 v20, v20, s0
	ds_write_b16 v59, v20 offset:7920
	v_lshlrev_b32_e32 v20, 16, v21
	s_waitcnt lgkmcnt(8)
	v_lshlrev_b32_e32 v21, 16, v29
	v_mul_f32_e32 v20, 0x3d800000, v20
	v_mul_f32_e32 v0, v0, v21
	v_mul_f32_e32 v20, v28, v20
	v_cvt_pk_bf16_f32 v0, v0, s0
	v_cvt_pk_bf16_f32 v20, v20, s0
	ds_write_b16 v59, v0 offset:42240
	v_add_f32_e32 v0, v95, v19
	ds_write_b16 v59, v20 offset:8448
	v_lshlrev_b32_e32 v20, 16, v22
	v_mul_f32_e32 v22, 0x3fb8aa3b, v0
	v_mul_f32_e32 v0, 0xbfb8aa3b, v0
	v_exp_f32_e32 v0, v0
	s_waitcnt lgkmcnt(9)
	v_lshlrev_b32_e32 v21, 16, v30
	v_exp_f32_e32 v22, v22
	v_mul_f32_e32 v20, 0x3d800000, v20
	v_mul_f32_e32 v0, v0, v21
	v_cvt_pk_bf16_f32 v0, v0, s0
	ds_write_b16 v59, v0 offset:42768
	v_add_f32_e32 v0, v96, v19
	v_mul_f32_e32 v20, v22, v20
	v_mul_f32_e32 v22, 0x3fb8aa3b, v0
	v_mul_f32_e32 v0, 0xbfb8aa3b, v0
	v_exp_f32_e32 v0, v0
	s_waitcnt lgkmcnt(9)
	v_lshlrev_b32_e32 v21, 16, v31
	v_exp_f32_e32 v22, v22
	v_cvt_pk_bf16_f32 v20, v20, s0
	v_mul_f32_e32 v0, v0, v21
	ds_write_b16 v59, v20 offset:8976
	v_lshlrev_b32_e32 v20, 16, v23
	v_cvt_pk_bf16_f32 v0, v0, s0
	v_mul_f32_e32 v20, 0x3d800000, v20
	ds_write_b16 v59, v0 offset:43296
	v_add_f32_e32 v0, v98, v19
	v_mul_f32_e32 v20, v22, v20
	v_mul_f32_e32 v22, 0x3fb8aa3b, v0
	v_mul_f32_e32 v0, 0xbfb8aa3b, v0
	v_exp_f32_e32 v0, v0
	s_waitcnt lgkmcnt(10)
	v_lshlrev_b32_e32 v21, 16, v32
	v_exp_f32_e32 v22, v22
	v_cvt_pk_bf16_f32 v20, v20, s0
	v_mul_f32_e32 v0, v0, v21
	ds_write_b16 v59, v20 offset:9504
	v_lshlrev_b32_e32 v20, 16, v24
	v_cvt_pk_bf16_f32 v0, v0, s0
	v_mul_f32_e32 v20, 0x3d800000, v20
	ds_write_b16 v59, v0 offset:43824
	v_add_f32_e32 v0, v97, v19
	v_mul_f32_e32 v20, v22, v20
	v_mul_f32_e32 v22, 0x3fb8aa3b, v0
	v_mul_f32_e32 v0, 0xbfb8aa3b, v0
	v_exp_f32_e32 v0, v0
	s_waitcnt lgkmcnt(11)
	v_lshlrev_b32_e32 v21, 16, v33
	v_exp_f32_e32 v22, v22
	v_cvt_pk_bf16_f32 v20, v20, s0
	v_mul_f32_e32 v0, v0, v21
	ds_write_b16 v59, v20 offset:10032
	v_lshlrev_b32_e32 v20, 16, v25
	v_cvt_pk_bf16_f32 v0, v0, s0
	v_mul_f32_e32 v20, 0x3d800000, v20
	ds_write_b16 v59, v0 offset:44352
	v_add_f32_e32 v0, v99, v19
	v_mul_f32_e32 v20, v22, v20
	v_mul_f32_e32 v22, 0x3fb8aa3b, v0
	v_mul_f32_e32 v0, 0xbfb8aa3b, v0
	v_exp_f32_e32 v0, v0
	s_waitcnt lgkmcnt(12)
	v_lshlrev_b32_e32 v21, 16, v34
	v_exp_f32_e32 v22, v22
	v_cvt_pk_bf16_f32 v20, v20, s0
	v_mul_f32_e32 v0, v0, v21
	ds_write_b16 v59, v20 offset:10560
	v_lshlrev_b32_e32 v20, 16, v26
	v_cvt_pk_bf16_f32 v0, v0, s0
	v_mul_f32_e32 v20, 0x3d800000, v20
	ds_write_b16 v59, v0 offset:44880
	v_add_f32_e32 v0, v100, v19
	v_mul_f32_e32 v20, v22, v20
	v_mul_f32_e32 v22, 0x3fb8aa3b, v0
	v_mul_f32_e32 v0, 0xbfb8aa3b, v0
	v_exp_f32_e32 v0, v0
	s_waitcnt lgkmcnt(13)
	v_lshlrev_b32_e32 v21, 16, v36
	v_exp_f32_e32 v22, v22
	v_cvt_pk_bf16_f32 v20, v20, s0
	v_mul_f32_e32 v0, v0, v21
	ds_write_b16 v59, v20 offset:11088
	v_lshlrev_b32_e32 v20, 16, v27
	v_cvt_pk_bf16_f32 v0, v0, s0
	v_mul_f32_e32 v20, 0x3d800000, v20
	ds_write_b16 v59, v0 offset:45408
	v_add_f32_e32 v0, v102, v19
	v_mul_f32_e32 v20, v22, v20
	v_mul_f32_e32 v37, 0x3fb8aa3b, v0
	v_mul_f32_e32 v0, 0xbfb8aa3b, v0
	v_cvt_pk_bf16_f32 v20, v20, s0
	v_exp_f32_e32 v0, v0
	ds_write_b16 v59, v20 offset:11616
	ds_read_u16 v20, v59 offset:12144
	ds_read_u16 v21, v59 offset:12672
	ds_read_u16 v22, v59 offset:13200
	ds_read_u16 v23, v59 offset:13728
	ds_read_u16 v24, v59 offset:14256
	ds_read_u16 v25, v59 offset:14784
	ds_read_u16 v26, v59 offset:15312
	ds_read_u16 v27, v59 offset:15840
	ds_read_u16 v28, v59 offset:45936
	ds_read_u16 v29, v59 offset:46464
	ds_read_u16 v30, v59 offset:46992
	ds_read_u16 v31, v59 offset:47520
	ds_read_u16 v32, v59 offset:48048
	ds_read_u16 v33, v59 offset:48576
	ds_read_u16 v34, v59 offset:49104
	ds_read_u16 v36, v59 offset:49632
	s_waitcnt lgkmcnt(7)
	v_lshlrev_b32_e32 v28, 16, v28
	v_mul_f32_e32 v0, v0, v28
	v_exp_f32_e32 v37, v37
	v_cvt_pk_bf16_f32 v0, v0, s0
	ds_write_b16 v59, v0 offset:45936
	v_add_f32_e32 v0, v101, v19
	v_lshlrev_b32_e32 v20, 16, v20
	v_mul_f32_e32 v28, 0x3fb8aa3b, v0
	v_mul_f32_e32 v0, 0xbfb8aa3b, v0
	v_mul_f32_e32 v20, 0x3d800000, v20
	v_exp_f32_e32 v0, v0
	v_mul_f32_e32 v20, v37, v20
	v_exp_f32_e32 v28, v28
	v_cvt_pk_bf16_f32 v20, v20, s0
	ds_write_b16 v59, v20 offset:12144
	v_lshlrev_b32_e32 v20, 16, v21
	s_waitcnt lgkmcnt(8)
	v_lshlrev_b32_e32 v21, 16, v29
	v_mul_f32_e32 v20, 0x3d800000, v20
	v_mul_f32_e32 v0, v0, v21
	v_mul_f32_e32 v20, v28, v20
	v_cvt_pk_bf16_f32 v0, v0, s0
	v_cvt_pk_bf16_f32 v20, v20, s0
	ds_write_b16 v59, v0 offset:46464
	v_add_f32_e32 v0, v103, v19
	ds_write_b16 v59, v20 offset:12672
	v_lshlrev_b32_e32 v20, 16, v22
	v_mul_f32_e32 v22, 0x3fb8aa3b, v0
	v_mul_f32_e32 v0, 0xbfb8aa3b, v0
	v_exp_f32_e32 v0, v0
	s_waitcnt lgkmcnt(9)
	v_lshlrev_b32_e32 v21, 16, v30
	v_exp_f32_e32 v22, v22
	v_mul_f32_e32 v20, 0x3d800000, v20
	v_mul_f32_e32 v0, v0, v21
	v_cvt_pk_bf16_f32 v0, v0, s0
	ds_write_b16 v59, v0 offset:46992
	v_add_f32_e32 v0, v104, v19
	v_mul_f32_e32 v20, v22, v20
	v_mul_f32_e32 v22, 0x3fb8aa3b, v0
	v_mul_f32_e32 v0, 0xbfb8aa3b, v0
	v_exp_f32_e32 v0, v0
	s_waitcnt lgkmcnt(9)
	v_lshlrev_b32_e32 v21, 16, v31
	v_exp_f32_e32 v22, v22
	v_cvt_pk_bf16_f32 v20, v20, s0
	v_mul_f32_e32 v0, v0, v21
	ds_write_b16 v59, v20 offset:13200
	v_lshlrev_b32_e32 v20, 16, v23
	v_cvt_pk_bf16_f32 v0, v0, s0
	v_mul_f32_e32 v20, 0x3d800000, v20
	ds_write_b16 v59, v0 offset:47520
	v_add_f32_e32 v0, v107, v19
	v_mul_f32_e32 v20, v22, v20
	v_mul_f32_e32 v22, 0x3fb8aa3b, v0
	v_mul_f32_e32 v0, 0xbfb8aa3b, v0
	v_exp_f32_e32 v0, v0
	s_waitcnt lgkmcnt(10)
	v_lshlrev_b32_e32 v21, 16, v32
	v_exp_f32_e32 v22, v22
	v_cvt_pk_bf16_f32 v20, v20, s0
	v_mul_f32_e32 v0, v0, v21
	ds_write_b16 v59, v20 offset:13728
	v_lshlrev_b32_e32 v20, 16, v24
	v_cvt_pk_bf16_f32 v0, v0, s0
	v_mul_f32_e32 v20, 0x3d800000, v20
	ds_write_b16 v59, v0 offset:48048
	v_add_f32_e32 v0, v106, v19
	v_mul_f32_e32 v20, v22, v20
	v_mul_f32_e32 v22, 0x3fb8aa3b, v0
	v_mul_f32_e32 v0, 0xbfb8aa3b, v0
	v_exp_f32_e32 v0, v0
	s_waitcnt lgkmcnt(11)
	v_lshlrev_b32_e32 v21, 16, v33
	v_exp_f32_e32 v22, v22
	v_cvt_pk_bf16_f32 v20, v20, s0
	v_mul_f32_e32 v0, v0, v21
	ds_write_b16 v59, v20 offset:14256
	v_lshlrev_b32_e32 v20, 16, v25
	v_cvt_pk_bf16_f32 v0, v0, s0
	v_mul_f32_e32 v20, 0x3d800000, v20
	ds_write_b16 v59, v0 offset:48576
	v_add_f32_e32 v0, v105, v19
	v_mul_f32_e32 v20, v22, v20
	v_mul_f32_e32 v22, 0x3fb8aa3b, v0
	v_mul_f32_e32 v0, 0xbfb8aa3b, v0
	v_exp_f32_e32 v0, v0
	s_waitcnt lgkmcnt(12)
	v_lshlrev_b32_e32 v21, 16, v34
	v_exp_f32_e32 v22, v22
	v_cvt_pk_bf16_f32 v20, v20, s0
	v_mul_f32_e32 v0, v0, v21
	ds_write_b16 v59, v20 offset:14784
	v_lshlrev_b32_e32 v20, 16, v26
	v_cvt_pk_bf16_f32 v0, v0, s0
	v_mul_f32_e32 v20, 0x3d800000, v20
	ds_write_b16 v59, v0 offset:49104
	v_add_f32_e32 v0, v109, v19
	v_mul_f32_e32 v20, v22, v20
	v_mul_f32_e32 v22, 0x3fb8aa3b, v0
	v_exp_f32_e32 v22, v22
	v_mul_f32_e32 v0, 0xbfb8aa3b, v0
	v_cvt_pk_bf16_f32 v20, v20, s0
	v_exp_f32_e32 v0, v0
	ds_write_b16 v59, v20 offset:15312
	v_lshlrev_b32_e32 v20, 16, v27
	v_mul_f32_e32 v20, 0x3d800000, v20
	s_waitcnt lgkmcnt(14)
	v_lshlrev_b32_e32 v21, 16, v36
	v_mul_f32_e32 v20, v22, v20
	v_cvt_pk_bf16_f32 v20, v20, s0
	v_mul_f32_e32 v0, v0, v21
	ds_write_b16 v59, v20 offset:15840
	ds_read_u16 v20, v59 offset:16368
	v_cvt_pk_bf16_f32 v0, v0, s0
	ds_write_b16 v59, v0 offset:49632
	v_add_f32_e32 v0, v19, v108
	v_mul_f32_e32 v21, 0x3fb8aa3b, v0
	v_mul_f32_e32 v0, 0xbfb8aa3b, v0
	v_exp_f32_e32 v21, v21
	v_exp_f32_e32 v0, v0
	s_waitcnt lgkmcnt(1)
	v_lshlrev_b32_e32 v19, 16, v20
	v_lshlrev_b32_e32 v20, 16, v35
	v_mul_f32_e32 v19, 0x3d800000, v19
	v_mul_f32_e32 v19, v21, v19
	v_mul_f32_e32 v0, v0, v20
	v_cvt_pk_bf16_f32 v19, v19, s0
	v_cvt_pk_bf16_f32 v0, v0, s0
	ds_write_b16 v59, v19 offset:16368
	ds_write_b16 v59, v0 offset:50160
	s_and_saveexec_b64 s[64:65], s[4:5]
	s_cbranch_execz .LBB0_613
	ds_read_b32 v0, v57 offset:1024
	s_ashr_i32 s37, s36, 31
	s_lshl_b64 s[66:67], s[36:37], 10
	s_waitcnt lgkmcnt(0)
	v_add_f32_e32 v0, v18, v0
	v_mul_f32_e32 v0, 0x3fb8aa3b, v0
	v_exp_f32_e32 v0, v0
	v_lshl_add_u64 v[18:19], v[62:63], 0, s[66:67]
	ds_write_b32 v51, v0
	global_store_dword v[18:19], v0, off
